# grid barrier: everybody polls the cross-XCC arrival counter (target = (gen+1)*nXCC); last leader's arrival releases directly, no generation atomic
# speedup vs baseline: 1.0089x; 1.0068x over previous
.LBB0_28:
	s_or_b64 exec, exec, s[2:3]
	v_cvt_f32_u32_e32 v4, v2
	s_waitcnt vmcnt(0)
	v_readfirstlane_b32 s2, v3
	v_sub_u32_e32 v3, 0, v2
	v_rcp_iflag_f32_e32 v4, v4
	v_add_u32_e32 v5, s2, v1
	v_mul_f32_e32 v4, 0x4f7ffffe, v4
	v_cvt_u32_f32_e32 v4, v4
	v_mul_lo_u32 v1, v3, v4
	v_mul_hi_u32 v1, v4, v1
	v_add_u32_e32 v1, v4, v1
	v_mul_hi_u32 v1, v5, v1
	v_mul_lo_u32 v3, v1, v2
	v_sub_u32_e32 v3, v5, v3
	v_add_u32_e32 v4, 1, v1
	v_cmp_ge_u32_e32 vcc, v3, v2
	s_nop 1
	v_cndmask_b32_e32 v1, v1, v4, vcc
	v_sub_u32_e32 v4, v3, v2
	v_cndmask_b32_e32 v3, v3, v4, vcc
	v_add_u32_e32 v4, 1, v1
	v_cmp_ge_u32_e32 vcc, v3, v2
	v_add_u32_e32 v3, 1, v5
	s_nop 0
	v_cndmask_b32_e32 v1, v1, v4, vcc
	v_mul_lo_u32 v4, v2, v1
	v_add_u32_e32 v2, v4, v2
	v_cmp_ne_u32_e32 vcc, v3, v2
	s_and_saveexec_b64 s[2:3], vcc
	s_xor_b64 s[2:3], exec, s[2:3]
	s_cbranch_execz .LBB0_42
	v_readlane_b32 s6, v254, 52
	v_readlane_b32 s7, v254, 53
	s_waitcnt lgkmcnt(0)
	s_nop 3
	v_add_u32_e32 v17, 1, v1
	v_mul_lo_u32 v17, v17, v0
	global_load_dword v0, v157, s[6:7] sc1
	s_waitcnt vmcnt(0)
	v_cmp_lt_u32_e32 vcc, v0, v17
	s_and_saveexec_b64 s[6:7], vcc
	s_cbranch_execz .LBB0_41
	s_mov_b32 s9, 1
	s_mov_b64 s[18:19], 0
	s_branch .LBB0_32

.LBB0_36:
	v_readlane_b32 s24, v254, 52
	v_readlane_b32 s25, v254, 53
	s_add_i32 s9, s9, 1
	s_mov_b64 s[26:27], -1
	s_nop 2
	global_load_dword v0, v157, s[24:25] sc1
	s_waitcnt vmcnt(0)
	v_cmp_ge_u32_e32 vcc, v0, v17
	s_orn2_b64 s[24:25], vcc, exec
	s_branch .LBB0_31

.LBB0_45:
	s_or_b64 exec, exec, s[6:7]
	v_cvt_f32_u32_e32 v3, v0
	s_waitcnt vmcnt(0)
	v_readfirstlane_b32 s2, v2
	s_mov_b64 s[6:7], 0
	v_rcp_iflag_f32_e32 v3, v3
	v_add_u32_e32 v1, s2, v1
	v_add_u32_e32 v4, 1, v1
	v_readlane_b32 s2, v254, 54
	v_mul_f32_e32 v2, 0x4f7ffffe, v3
	v_cvt_u32_f32_e32 v2, v2
	v_sub_u32_e32 v3, 0, v0
	v_readlane_b32 s3, v254, 55
	v_mul_lo_u32 v3, v3, v2
	v_mul_hi_u32 v3, v2, v3
	v_add_u32_e32 v2, v2, v3
	v_mul_hi_u32 v2, v1, v2
	v_mul_lo_u32 v3, v2, v0
	v_sub_u32_e32 v1, v1, v3
	v_add_u32_e32 v5, 1, v2
	v_cmp_ge_u32_e32 vcc, v1, v0
	v_sub_u32_e32 v3, v1, v0
	s_nop 0
	v_cndmask_b32_e32 v2, v2, v5, vcc
	v_cndmask_b32_e32 v1, v1, v3, vcc
	v_add_u32_e32 v3, 1, v2
	v_cmp_ge_u32_e32 vcc, v1, v0
	s_nop 1
	v_cndmask_b32_e32 v2, v2, v3, vcc
	v_mul_lo_u32 v1, v0, v2
	v_add_u32_e32 v0, v1, v0
	v_mov_b32_e32 v17, v0
	v_cmp_ne_u32_e32 vcc, v4, v0
	v_mov_b64_e32 v[0:1], s[2:3]
	s_and_saveexec_b64 s[2:3], vcc
	s_cbranch_execz .LBB0_57
	v_readlane_b32 s6, v254, 52
	v_readlane_b32 s7, v254, 53
	s_mov_b64 s[18:19], 0
	s_nop 3
	global_load_dword v0, v157, s[6:7] sc1
	s_waitcnt vmcnt(0)
	v_cmp_lt_u32_e32 vcc, v0, v17
	s_and_saveexec_b64 s[6:7], vcc
	s_cbranch_execz .LBB0_56
	s_mov_b32 s9, 1
	s_branch .LBB0_49
